# up GEMM: next-unit scheduler block (tile decode + pointers) moved from the unit header into the first phase's load segment, in the shadow of its waits
# speedup vs baseline: 1.0025x; 1.0005x over previous
; #define PG8_STAGE(bufoff, gbase, voff) do { _Pragma("unroll") for (int _i = 0; _i < 2; ++_i) \
;         __builtin_amdgcn_global_load_lds((const unsigned*)((const char*)(gbase) + (voff)[_i]), (LAS unsigned*)(lds + (bufoff) + ldsw + _i * 8192), 16, 0, 0); } while (0)
; #define PG8_LDA(dst, b, h) do { _Pragma("unroll") for (int m = 0; m < 4; ++m) _Pragma("unroll") for (int k = 0; k < 2; ++k) dst[m][k] = *(const LAS bf16x8*)(lds + PG8_SA(b, h) + aoff + m * 2048 + k * 1024); } while (0)
; #define PG8_LDB(dst, b, h) do { _Pragma("unroll") for (int n = 0; n < 2; ++n) _Pragma("unroll") for (int k = 0; k < 2; ++k) dst[n][k] = *(const LAS bf16x8*)(lds + PG8_SB(b, h) + boff + n * 2048 + k * 1024); } while (0)
; #define PG8_SCHED __builtin_amdgcn_sched_barrier(0)
;     __device__ __forceinline__ const char* a(const pg8::Unit& u) const { return (const char*)ws + aoff + (size_t)u.pm * 256 * K_ * 2 + (u.kq < 0 ? 0 : u.kq * (K_ / 4) * 2); }
;     __device__ __forceinline__ const char* b(const pg8::Unit& u) const { return (const char*)ws + boff + (size_t)u.pn * 256 * K_ * 2 + (u.kq < 0 ? 0 : u.kq * (K_ / 4) * 2); }
;     __device__ __forceinline__ bool next(int i, pg8::Unit& u) const { return pg8::tile2d<44>(i, nM, u); }
;     __device__ __forceinline__ const char* a(const pg8::Unit& u) const { return (const char*)ws + WS_A + (size_t)u.pm * 256 * D * 2; }
;     __device__ __forceinline__ bool next(int i, pg8::Unit& u) const { return pg8::tile2d<72>(i, 16, u); }
; template <class Epi, class Sched, bool ALIGN_EPI>
; __device__ __forceinline__ void gemm_phase(LAS unsigned char* lds, const int wid, const int lda_, const int ldb_, const int K_, const Sched& S, const Epi& E) {
;     ...
;         const bool has_next = S.next(ui + 1, nxt);
;         const int nt = S.nt(cur);
;         const char* nA = has_next ? S.a(nxt) : cA; const char* nB = has_next ? S.b(nxt) : cB;
; #pragma unroll 1
;         for (int t = 0; t < nt; t += 2) {
;             const bool last = (t == nt - 2);
;             const char* a1 = cA + (size_t)(t + 1) * kstep;
;             const char* a2 = last ? nA : cA + (size_t)(t + 2) * kstep; const char* b2 = last ? nB : cB + (size_t)(t + 2) * kstep;
;             const char* a3 = a2 + kstep; const char* b3 = b2 + kstep;
;             PG8_LDB(B0, 0, 0); PG8_LDB(B1, 0, 1); PG8_SCHED; PG8_LDA(At, 0, 0); PG8_STAGE(PG8_SA(1, 1), a1 + hstepA, voffA);
.LBB0_1117:
	s_add_u32 s76, s40, 0x80
	s_addc_u32 s77, s41, 0
	v_lshl_add_u64 v[156:157], s[76:77], 0, v[152:153]
	v_lshl_add_u64 v[158:159], s[76:77], 0, v[154:155]
	s_add_u32 s76, s50, 0x100
	s_addc_u32 s77, s51, 0
	s_mov_b32 s78, -2
	s_mov_b64 s[50:51], 0
	s_add_u32 s17, s40, s50
	s_addc_u32 s27, s41, s51
	s_add_u32 s17, s17, 0x100
	s_addc_u32 s27, s27, 0
	s_add_u32 s79, s76, s50
	s_addc_u32 s80, s77, s51
	s_add_i32 s86, 0, 0x10000
	s_cmpk_eq_i32 s50, 0xf00
	s_cselect_b32 s95, s4, s27
	s_cselect_b32 s94, s5, s17
	v_add_u32_e32 v141, s86, v135
	s_cselect_b32 s81, s43, s80
	s_cselect_b32 s80, s45, s79
	s_add_i32 s17, 0, 0x14000
	ds_read_b128 v[160:163], v141
	ds_read_b128 v[164:167], v141 offset:1024
	ds_read_b128 v[168:171], v141 offset:2048
	ds_read_b128 v[172:175], v141 offset:3072
	v_add_u32_e32 v141, s17, v135
	ds_read_b128 v[180:183], v141
	ds_read_b128 v[184:187], v141 offset:1024
	ds_read_b128 v[188:191], v141 offset:2048
	ds_read_b128 v[192:195], v141 offset:3072
	v_lshl_add_u64 v[228:229], v[158:159], 0, s[50:51]
	s_add_i32 m0, s16, 0xc000
	ds_read_b128 v[196:199], v139
	ds_read_b128 v[200:203], v139 offset:1024
	ds_read_b128 v[204:207], v139 offset:2048
	ds_read_b128 v[208:211], v139 offset:3072
	ds_read_b128 v[212:215], v139 offset:4096
	ds_read_b128 v[216:219], v139 offset:5120
	ds_read_b128 v[220:223], v139 offset:6144
	ds_read_b128 v[224:227], v139 offset:7168
	global_load_lds_dwordx4 v[228:229], off
	v_lshl_add_u64 v[228:229], v[156:157], 0, s[50:51]
	s_add_i32 m0, s16, 0xe000
	s_nop 0
	global_load_lds_dwordx4 v[228:229], off
	v_writelane_b32 v255, s17, 46
	s_add_i32 s75, s75, 1
	s_mul_i32 s4, s91, s75
	s_mul_hi_u32 s5, s90, s75
	s_add_i32 s5, s5, s4
	s_mul_i32 s4, s90, s75
	s_add_u32 s4, s4, s2
	v_readlane_b32 s17, v252, 52
	s_addc_u32 s5, s5, s17
	v_mov_b64_e32 v[0:1], s[0:1]
	v_cmp_ge_i64_e64 s[36:37], s[4:5], v[0:1]
	s_and_b64 vcc, exec, s[36:37]
	s_cbranch_vccnz .LBB0_1119
	s_ashr_i32 s17, s4, 31
	s_lshr_b32 s17, s17, 29
	s_add_i32 s17, s4, s17
	s_ashr_i32 s27, s17, 3
	s_and_b32 s17, s17, -8
	s_sub_i32 s17, s4, s17
	s_cmp_lt_i32 s17, 0
	s_cselect_b32 s42, s14, s7
	s_mul_i32 s17, s42, s17
	s_add_i32 s17, s17, s27
	s_mul_hi_i32 s27, s17, 0x2e8ba2e9
	s_lshr_b32 s42, s27, 31
	s_ashr_i32 s27, s27, 6
	s_add_i32 s27, s27, s42
	s_lshl_b32 s43, s27, 3
	s_sub_i32 s42, s6, s43
	s_min_i32 s44, s42, 8
	s_abs_i32 s42, s44
	v_cvt_f32_u32_e32 v0, s42
	s_sub_i32 s46, 0, s42
	s_mulk_i32 s27, 0x160
	s_sub_i32 s17, s17, s27
	v_rcp_iflag_f32_e32 v0, v0
	s_abs_i32 s27, s17
	s_xor_b32 s45, s17, s44
	s_ashr_i32 s45, s45, 31
	v_mul_f32_e32 v0, 0x4f7ffffe, v0
	v_cvt_u32_f32_e32 v0, v0
	s_nop 0
	v_readfirstlane_b32 s47, v0
	s_mul_i32 s46, s46, s47
	s_mul_hi_u32 s46, s47, s46
	s_add_i32 s47, s47, s46
	s_mul_hi_u32 s46, s27, s47
	s_mul_i32 s47, s46, s42
	s_sub_i32 s27, s27, s47
	s_add_i32 s48, s46, 1
	s_sub_i32 s47, s27, s42
	s_cmp_ge_u32 s27, s42
	s_cselect_b32 s46, s48, s46
	s_cselect_b32 s27, s47, s27
	s_add_i32 s47, s46, 1
	s_cmp_ge_u32 s27, s42
	s_cselect_b32 s27, s47, s46
	s_xor_b32 s27, s27, s45
	s_sub_i32 s42, s27, s45
	s_mul_i32 s27, s42, s44
	s_sub_i32 s17, s17, s27
	s_add_i32 s44, s17, s43
	s_add_i32 s42, s42, 22
	s_cmp_ge_i32 s42, 44
	s_cselect_b32 s100, 44, 0
	s_sub_i32 s42, s42, s100
; #define PG8_STAGE(bufoff, gbase, voff) do { _Pragma("unroll") for (int _i = 0; _i < 2; ++_i) \
;         __builtin_amdgcn_global_load_lds((const unsigned*)((const char*)(gbase) + (voff)[_i]), (LAS unsigned*)(lds + (bufoff) + ldsw + _i * 8192), 16, 0, 0); } while (0)
; #define PG8_LDA(dst, b, h) do { _Pragma("unroll") for (int m = 0; m < 4; ++m) _Pragma("unroll") for (int k = 0; k < 2; ++k) dst[m][k] = *(const LAS bf16x8*)(lds + PG8_SA(b, h) + aoff + m * 2048 + k * 1024); } while (0)
; #define PG8_LDB(dst, b, h) do { _Pragma("unroll") for (int n = 0; n < 2; ++n) _Pragma("unroll") for (int k = 0; k < 2; ++k) dst[n][k] = *(const LAS bf16x8*)(lds + PG8_SB(b, h) + boff + n * 2048 + k * 1024); } while (0)
; #define PG8_MMA(ai, bj, At, Bt) do { __builtin_amdgcn_s_setprio(1); _Pragma("unroll") for (int m = 0; m < 4; ++m) _Pragma("unroll") for (int n = 0; n < 2; ++n) _Pragma("unroll") for (int k = 0; k < 2; ++k) \
;         acc[ai][bj][m][n] = __builtin_amdgcn_mfma_f32_16x16x32_bf16(Bt[n][k], At[m][k], acc[ai][bj][m][n], 0, 0, 0); __builtin_amdgcn_s_setprio(0); } while (0)
; #define PG8_WAIT_V(n) asm volatile("s_waitcnt vmcnt(" #n ")" ::: "memory")
; template <class Epi, class Sched, bool ALIGN_EPI>
; __device__ __forceinline__ void gemm_phase(LAS unsigned char* lds, const int wid, const int lda_, const int ldb_, const int K_, const Sched& S, const Epi& E) {
;     ...
;         const char* nA = has_next ? S.a(nxt) : cA; const char* nB = has_next ? S.b(nxt) : cB;
; #pragma unroll 1
;         for (int t = 0; t < nt; t += 2) {
;             const bool last = (t == nt - 2);
;             const char* a1 = cA + (size_t)(t + 1) * kstep;
;             const char* a2 = last ? nA : cA + (size_t)(t + 2) * kstep; const char* b2 = last ? nB : cB + (size_t)(t + 2) * kstep;
;             const char* a3 = a2 + kstep; const char* b3 = b2 + kstep;
;             PG8_LDB(B0, 0, 0); PG8_LDB(B1, 0, 1); PG8_SCHED; PG8_LDA(At, 0, 0); PG8_STAGE(PG8_SA(1, 1), a1 + hstepA, voffA);
;             PG8_WAIT_V(8); PG8_WAIT_L(0); PG8_BAR; PG8_MMA(0, 0, At, B0); PG8_MMA(0, 1, At, B1); PG8_BAR; PG8_SCHED;
;             PG8_LDA(At, 0, 1); PG8_STAGE(PG8_SB(0, 0), b2, voffB); PG8_STAGE(PG8_SB(0, 1), b2 + hstepB, voffB); PG8_STAGE(PG8_SA(0, 0), a2, voffA);
;             PG8_WAIT_V(8); PG8_WAIT_L(0); PG8_BAR; PG8_MMA(1, 0, At, B0); PG8_MMA(1, 1, At, B1); PG8_BAR; PG8_SCHED;
.LBB0_1119:
	v_mov_b64_e32 v[0:1], s[0:1]
	s_ashr_i32 s45, s44, 31
	v_cmp_lt_i64_e32 vcc, s[4:5], v[0:1]
	s_lshl_b64 s[4:5], s[44:45], 20
	v_readlane_b32 s46, v253, 52
	v_readlane_b32 s47, v253, 53
	s_add_u32 s46, s46, s4
	s_addc_u32 s47, s47, s5
	s_and_b64 s[4:5], vcc, exec
	s_cselect_b32 s4, s47, s41
	s_cselect_b32 s5, s46, s40
	s_ashr_i32 s43, s42, 31
	s_lshl_b64 s[48:49], s[42:43], 20
	s_add_u32 s48, s15, s48
	s_addc_u32 s49, s26, s49
	s_and_b64 s[100:101], vcc, exec
	s_cselect_b32 s43, s49, s77
	s_cselect_b32 s45, s48, s76
	s_nop 0
	v_readlane_b32 s17, v255, 46
	s_waitcnt vmcnt(8)
	s_waitcnt lgkmcnt(0)
	s_barrier
	s_setprio 1
	s_waitcnt lgkmcnt(0)
	v_mfma_f32_16x16x32_bf16 v[124:127], v[160:163], v[196:199], 0
	v_mfma_f32_16x16x32_bf16 v[120:123], v[168:171], v[196:199], 0
	v_mfma_f32_16x16x32_bf16 v[116:119], v[160:163], v[204:207], 0
	v_mfma_f32_16x16x32_bf16 v[112:115], v[168:171], v[204:207], 0
	v_mfma_f32_16x16x32_bf16 v[100:103], v[160:163], v[212:215], 0
	v_mfma_f32_16x16x32_bf16 v[96:99], v[168:171], v[212:215], 0
	v_mfma_f32_16x16x32_bf16 v[84:87], v[160:163], v[220:223], 0
	v_mfma_f32_16x16x32_bf16 v[80:83], v[168:171], v[220:223], 0
	v_mfma_f32_16x16x32_bf16 v[124:127], v[164:167], v[200:203], v[124:127]
	v_mfma_f32_16x16x32_bf16 v[120:123], v[172:175], v[200:203], v[120:123]
	v_mfma_f32_16x16x32_bf16 v[116:119], v[164:167], v[208:211], v[116:119]
	v_mfma_f32_16x16x32_bf16 v[112:115], v[172:175], v[208:211], v[112:115]
	v_mfma_f32_16x16x32_bf16 v[100:103], v[164:167], v[216:219], v[100:103]
	v_mfma_f32_16x16x32_bf16 v[96:99], v[172:175], v[216:219], v[96:99]
	v_mfma_f32_16x16x32_bf16 v[84:87], v[164:167], v[224:227], v[84:87]
	v_mfma_f32_16x16x32_bf16 v[80:83], v[172:175], v[224:227], v[80:83]
	s_setprio 0
	s_setprio 1
	v_mfma_f32_16x16x32_bf16 v[108:111], v[180:183], v[196:199], 0
	v_mfma_f32_16x16x32_bf16 v[104:107], v[188:191], v[196:199], 0
	v_mfma_f32_16x16x32_bf16 v[92:95], v[180:183], v[204:207], 0
	v_mfma_f32_16x16x32_bf16 v[88:91], v[188:191], v[204:207], 0
	v_mfma_f32_16x16x32_bf16 v[76:79], v[180:183], v[212:215], 0
	v_mfma_f32_16x16x32_bf16 v[72:75], v[188:191], v[212:215], 0
	v_mfma_f32_16x16x32_bf16 v[68:71], v[180:183], v[220:223], 0
	v_mfma_f32_16x16x32_bf16 v[64:67], v[188:191], v[220:223], 0
	v_mfma_f32_16x16x32_bf16 v[108:111], v[184:187], v[200:203], v[108:111]
	v_mfma_f32_16x16x32_bf16 v[104:107], v[192:195], v[200:203], v[104:107]
	v_mfma_f32_16x16x32_bf16 v[92:95], v[184:187], v[208:211], v[92:95]
	v_mfma_f32_16x16x32_bf16 v[88:91], v[192:195], v[208:211], v[88:91]
	v_mfma_f32_16x16x32_bf16 v[76:79], v[184:187], v[216:219], v[76:79]
	v_mfma_f32_16x16x32_bf16 v[72:75], v[192:195], v[216:219], v[72:75]
	v_mfma_f32_16x16x32_bf16 v[68:71], v[184:187], v[224:227], v[68:71]
	v_mfma_f32_16x16x32_bf16 v[64:67], v[192:195], v[224:227], v[64:67]
	s_setprio 0
	s_barrier
	s_add_i32 s27, s86, s3
	v_lshl_add_u64 v[228:229], s[80:81], 0, v[176:177]
	s_mov_b32 m0, s27
	ds_read_b128 v[196:199], v139 offset:16384
	ds_read_b128 v[200:203], v139 offset:17408
	ds_read_b128 v[204:207], v139 offset:18432
	ds_read_b128 v[208:211], v139 offset:19456
	ds_read_b128 v[212:215], v139 offset:20480
	ds_read_b128 v[216:219], v139 offset:21504
	ds_read_b128 v[220:223], v139 offset:22528
	ds_read_b128 v[224:227], v139 offset:23552
	global_load_lds_dwordx4 v[228:229], off
	s_add_i32 m0, s27, 0x2000
	v_lshl_add_u64 v[230:231], s[80:81], 0, v[128:129]
	s_add_u32 s80, s80, s30
	s_addc_u32 s81, s81, s31
	s_add_i32 s17, s17, s3
	global_load_lds_dwordx4 v[230:231], off
	v_lshl_add_u64 v[232:233], s[80:81], 0, v[176:177]
	s_mov_b32 m0, s17
	v_lshl_add_u64 v[234:235], s[80:81], 0, v[128:129]
	global_load_lds_dwordx4 v[232:233], off
	s_add_i32 m0, s17, 0x2000
	v_lshl_add_u64 v[236:237], s[94:95], 0, v[132:133]
	global_load_lds_dwordx4 v[234:235], off
	s_mov_b32 m0, s16
	v_lshl_add_u64 v[246:247], s[94:95], 0, v[130:131]
	global_load_lds_dwordx4 v[236:237], off
	s_mov_b32 m0, s35
	s_nop 0
	global_load_lds_dwordx4 v[246:247], off
	s_waitcnt vmcnt(8)
	s_waitcnt lgkmcnt(0)
	s_barrier
	s_setprio 1
	s_waitcnt lgkmcnt(0)
	v_mfma_f32_16x16x32_bf16 v[60:63], v[160:163], v[196:199], 0
	v_mfma_f32_16x16x32_bf16 v[56:59], v[168:171], v[196:199], 0
	v_mfma_f32_16x16x32_bf16 v[52:55], v[160:163], v[204:207], 0
	v_mfma_f32_16x16x32_bf16 v[48:51], v[168:171], v[204:207], 0
	v_mfma_f32_16x16x32_bf16 v[36:39], v[160:163], v[212:215], 0
	v_mfma_f32_16x16x32_bf16 v[32:35], v[168:171], v[212:215], 0
	v_mfma_f32_16x16x32_bf16 v[20:23], v[160:163], v[220:223], 0
	v_mfma_f32_16x16x32_bf16 v[16:19], v[168:171], v[220:223], 0
	v_mfma_f32_16x16x32_bf16 v[60:63], v[164:167], v[200:203], v[60:63]
	v_mfma_f32_16x16x32_bf16 v[56:59], v[172:175], v[200:203], v[56:59]
	v_mfma_f32_16x16x32_bf16 v[52:55], v[164:167], v[208:211], v[52:55]
	v_mfma_f32_16x16x32_bf16 v[48:51], v[172:175], v[208:211], v[48:51]
	v_mfma_f32_16x16x32_bf16 v[36:39], v[164:167], v[216:219], v[36:39]
	v_mfma_f32_16x16x32_bf16 v[32:35], v[172:175], v[216:219], v[32:35]
	v_mfma_f32_16x16x32_bf16 v[20:23], v[164:167], v[224:227], v[20:23]
	v_mfma_f32_16x16x32_bf16 v[16:19], v[172:175], v[224:227], v[16:19]
	s_setprio 0
	s_setprio 1
	v_mfma_f32_16x16x32_bf16 v[44:47], v[180:183], v[196:199], 0
	v_mfma_f32_16x16x32_bf16 v[40:43], v[188:191], v[196:199], 0
	v_mfma_f32_16x16x32_bf16 v[28:31], v[180:183], v[204:207], 0
	v_mfma_f32_16x16x32_bf16 v[24:27], v[188:191], v[204:207], 0
	v_mfma_f32_16x16x32_bf16 v[12:15], v[180:183], v[212:215], 0
	v_mfma_f32_16x16x32_bf16 v[8:11], v[188:191], v[212:215], 0
	v_mfma_f32_16x16x32_bf16 v[4:7], v[180:183], v[220:223], 0
	v_mfma_f32_16x16x32_bf16 v[0:3], v[188:191], v[220:223], 0
	v_mfma_f32_16x16x32_bf16 v[44:47], v[184:187], v[200:203], v[44:47]
	v_mfma_f32_16x16x32_bf16 v[40:43], v[192:195], v[200:203], v[40:43]
	v_mfma_f32_16x16x32_bf16 v[28:31], v[184:187], v[208:211], v[28:31]
	v_mfma_f32_16x16x32_bf16 v[24:27], v[192:195], v[208:211], v[24:27]
	v_mfma_f32_16x16x32_bf16 v[12:15], v[184:187], v[216:219], v[12:15]
	v_mfma_f32_16x16x32_bf16 v[8:11], v[192:195], v[216:219], v[8:11]
	v_mfma_f32_16x16x32_bf16 v[4:7], v[184:187], v[224:227], v[4:7]
	v_mfma_f32_16x16x32_bf16 v[0:3], v[192:195], v[224:227], v[0:3]
	s_setprio 0
	s_barrier
	s_branch .Lgemm_join_1120
